# v47: + rope_item loop 2 (both copies) unrolled with both iterations' loads issued first
# speedup vs baseline: 1.0024x; 1.0021x over previous
.LBB0_1485:
	s_mov_b32 s5, 0x0
	v_add_u32_e32 v0, s5, v8
	v_ashrrev_i32_e32 v0, 4, v0
	v_add_u32_e32 v34, s16, v0
	v_lshl_or_b32 v18, v34, 5, v2
	v_add_u32_e32 v0, s3, v0
	v_ashrrev_i32_e32 v19, 31, v18
	v_mad_i64_i32 v[14:15], s[0:1], v0, s84, v[4:5]
	v_lshlrev_b64 v[18:19], 2, v[18:19]
	global_load_dwordx4 v[10:13], v[14:15], off
	s_nop 0
	global_load_dwordx4 v[14:17], v[14:15], off offset:64
	v_lshl_add_u64 v[22:23], s[8:9], 0, v[18:19]
	v_lshl_add_u64 v[30:31], s[10:11], 0, v[18:19]
	global_load_dwordx4 v[18:21], v[22:23], off offset:16
	s_nop 0
	global_load_dwordx4 v[22:25], v[22:23], off
	s_nop 0
	global_load_dwordx4 v[26:29], v[30:31], off offset:16
	s_nop 0
	global_load_dwordx4 v[30:33], v[30:31], off
	v_ashrrev_i32_e32 v35, 31, v34
	s_mov_b32 s5, 0x200
	v_add_u32_e32 v50, s5, v8
	v_ashrrev_i32_e32 v50, 4, v50
	v_add_u32_e32 v84, s16, v50
	v_lshl_or_b32 v68, v84, 5, v2
	v_add_u32_e32 v50, s3, v50
	v_ashrrev_i32_e32 v69, 31, v68
	v_mad_i64_i32 v[64:65], s[0:1], v50, s84, v[4:5]
	v_lshlrev_b64 v[68:69], 2, v[68:69]
	global_load_dwordx4 v[60:63], v[64:65], off
	s_nop 0
	global_load_dwordx4 v[64:67], v[64:65], off offset:64
	v_lshl_add_u64 v[72:73], s[8:9], 0, v[68:69]
	v_lshl_add_u64 v[80:81], s[10:11], 0, v[68:69]
	global_load_dwordx4 v[68:71], v[72:73], off offset:16
	s_nop 0
	global_load_dwordx4 v[72:75], v[72:73], off
	s_nop 0
	global_load_dwordx4 v[76:79], v[80:81], off offset:16
	s_nop 0
	global_load_dwordx4 v[80:83], v[80:81], off
	v_ashrrev_i32_e32 v85, 31, v84
	s_waitcnt vmcnt(6)
	v_lshlrev_b32_e32 v36, 16, v10
	v_and_b32_e32 v37, 0xffff0000, v10
	v_lshlrev_b32_e32 v38, 16, v14
	v_and_b32_e32 v39, 0xffff0000, v14
	v_pk_mul_f32 v[40:41], v[30:31], v[38:39]
	v_pk_mul_f32 v[30:31], v[30:31], v[36:37]
	v_lshlrev_b32_e32 v14, 16, v15
	v_and_b32_e32 v15, 0xffff0000, v15
	v_pk_fma_f32 v[40:41], v[22:23], v[36:37], v[40:41] neg_lo:[0,0,1] neg_hi:[0,0,1]
	v_pk_fma_f32 v[22:23], v[22:23], v[38:39], v[30:31]
	v_lshlrev_b32_e32 v10, 16, v11
	v_and_b32_e32 v11, 0xffff0000, v11
	v_pk_mul_f32 v[30:31], v[32:33], v[14:15]
	s_nop 0
	v_pk_fma_f32 v[30:31], v[24:25], v[10:11], v[30:31] neg_lo:[0,0,1] neg_hi:[0,0,1]
	v_pk_mul_f32 v[10:11], v[32:33], v[10:11]
	s_nop 0
	v_pk_fma_f32 v[14:15], v[24:25], v[14:15], v[10:11]
	v_lshlrev_b32_e32 v24, 16, v16
	v_and_b32_e32 v25, 0xffff0000, v16
	v_lshlrev_b32_e32 v10, 16, v12
	v_and_b32_e32 v11, 0xffff0000, v12
	v_pk_mul_f32 v[32:33], v[26:27], v[24:25]
	v_lshlrev_b32_e32 v12, 16, v17
	v_pk_fma_f32 v[32:33], v[18:19], v[10:11], v[32:33] neg_lo:[0,0,1] neg_hi:[0,0,1]
	v_pk_mul_f32 v[10:11], v[26:27], v[10:11]
	s_nop 0
	v_pk_fma_f32 v[18:19], v[18:19], v[24:25], v[10:11]
	v_lshlrev_b32_e32 v10, 16, v13
	v_and_b32_e32 v11, 0xffff0000, v13
	v_and_b32_e32 v13, 0xffff0000, v17
	v_pk_mul_f32 v[16:17], v[28:29], v[12:13]
	s_nop 0
	v_pk_fma_f32 v[16:17], v[20:21], v[10:11], v[16:17] neg_lo:[0,0,1] neg_hi:[0,0,1]
	v_pk_mul_f32 v[10:11], v[28:29], v[10:11]
	s_nop 0
	v_pk_fma_f32 v[20:21], v[20:21], v[12:13], v[10:11]
	v_lshlrev_b64 v[10:11], 7, v[34:35]
	v_lshl_add_u64 v[24:25], v[6:7], 0, v[10:11]
	v_cvt_pk_bf16_f32 v10, v40, v41
	v_cvt_pk_bf16_f32 v11, v30, v31
	v_cvt_pk_bf16_f32 v12, v32, v33
	v_cvt_pk_bf16_f32 v13, v16, v17
	global_store_dwordx4 v[24:25], v[10:13], off
	s_nop 1
	v_cvt_pk_bf16_f32 v10, v22, v23
	v_cvt_pk_bf16_f32 v11, v14, v15
	v_cvt_pk_bf16_f32 v12, v18, v19
	v_cvt_pk_bf16_f32 v13, v20, v21
	global_store_dwordx4 v[24:25], v[10:13], off offset:64
	s_waitcnt vmcnt(2)
	v_lshlrev_b32_e32 v86, 16, v60
	v_and_b32_e32 v87, 0xffff0000, v60
	v_lshlrev_b32_e32 v88, 16, v64
	v_and_b32_e32 v89, 0xffff0000, v64
	v_pk_mul_f32 v[90:91], v[80:81], v[88:89]
	v_pk_mul_f32 v[80:81], v[80:81], v[86:87]
	v_lshlrev_b32_e32 v64, 16, v65
	v_and_b32_e32 v65, 0xffff0000, v65
	v_pk_fma_f32 v[90:91], v[72:73], v[86:87], v[90:91] neg_lo:[0,0,1] neg_hi:[0,0,1]
	v_pk_fma_f32 v[72:73], v[72:73], v[88:89], v[80:81]
	v_lshlrev_b32_e32 v60, 16, v61
	v_and_b32_e32 v61, 0xffff0000, v61
	v_pk_mul_f32 v[80:81], v[82:83], v[64:65]
	s_nop 0
	v_pk_fma_f32 v[80:81], v[74:75], v[60:61], v[80:81] neg_lo:[0,0,1] neg_hi:[0,0,1]
	v_pk_mul_f32 v[60:61], v[82:83], v[60:61]
	s_nop 0
	v_pk_fma_f32 v[64:65], v[74:75], v[64:65], v[60:61]
	v_lshlrev_b32_e32 v74, 16, v66
	v_and_b32_e32 v75, 0xffff0000, v66
	v_lshlrev_b32_e32 v60, 16, v62
	v_and_b32_e32 v61, 0xffff0000, v62
	v_pk_mul_f32 v[82:83], v[76:77], v[74:75]
	v_lshlrev_b32_e32 v62, 16, v67
	v_pk_fma_f32 v[82:83], v[68:69], v[60:61], v[82:83] neg_lo:[0,0,1] neg_hi:[0,0,1]
	v_pk_mul_f32 v[60:61], v[76:77], v[60:61]
	s_nop 0
	v_pk_fma_f32 v[68:69], v[68:69], v[74:75], v[60:61]
	v_lshlrev_b32_e32 v60, 16, v63
	v_and_b32_e32 v61, 0xffff0000, v63
	v_and_b32_e32 v63, 0xffff0000, v67
	v_pk_mul_f32 v[66:67], v[78:79], v[62:63]
	s_nop 0
	v_pk_fma_f32 v[66:67], v[70:71], v[60:61], v[66:67] neg_lo:[0,0,1] neg_hi:[0,0,1]
	v_pk_mul_f32 v[60:61], v[78:79], v[60:61]
	s_nop 0
	v_pk_fma_f32 v[70:71], v[70:71], v[62:63], v[60:61]
	v_lshlrev_b64 v[60:61], 7, v[84:85]
	v_lshl_add_u64 v[74:75], v[6:7], 0, v[60:61]
	v_cvt_pk_bf16_f32 v60, v90, v91
	v_cvt_pk_bf16_f32 v61, v80, v81
	v_cvt_pk_bf16_f32 v62, v82, v83
	v_cvt_pk_bf16_f32 v63, v66, v67
	global_store_dwordx4 v[74:75], v[60:63], off
	s_nop 1
	v_cvt_pk_bf16_f32 v60, v72, v73
	v_cvt_pk_bf16_f32 v61, v64, v65
	v_cvt_pk_bf16_f32 v62, v68, v69
	v_cvt_pk_bf16_f32 v63, v70, v71
	global_store_dwordx4 v[74:75], v[60:63], off offset:64
	s_movk_i32 s5, 0x200
	s_mov_b64 s[0:1], 0
	s_mov_b64 vcc, exec
	v_ashrrev_i32_e32 v4, 3, v8
	v_add_u32_e32 v0, s3, v4
	v_mov_b64_e32 v[2:3], s[50:51]
	v_and_b32_e32 v6, 7, v8
	v_mad_i64_i32 v[2:3], s[0:1], v0, s84, v[2:3]
	v_and_b32_e32 v0, 56, v9
	v_mul_lo_u32 v5, v4, s45
	v_lshlrev_b32_e32 v7, 4, v6
	v_add3_u32 v5, v5, v7, 0
	s_mov_b32 s0, 0
	v_lshlrev_b32_e32 v0, 1, v0
	s_mov_b32 s1, 0

.LBB0_1557:
	s_mov_b32 s4, 0x0
	v_add_u32_e32 v0, s4, v8
	v_ashrrev_i32_e32 v0, 4, v0
	v_add_u32_e32 v34, s16, v0
	v_lshl_or_b32 v18, v34, 5, v2
	v_add_u32_e32 v0, s2, v0
	v_ashrrev_i32_e32 v19, 31, v18
	v_mad_i64_i32 v[14:15], s[0:1], v0, s84, v[4:5]
	v_lshlrev_b64 v[18:19], 2, v[18:19]
	global_load_dwordx4 v[10:13], v[14:15], off
	s_nop 0
	global_load_dwordx4 v[14:17], v[14:15], off offset:64
	v_lshl_add_u64 v[22:23], s[8:9], 0, v[18:19]
	v_lshl_add_u64 v[30:31], s[10:11], 0, v[18:19]
	global_load_dwordx4 v[18:21], v[22:23], off offset:16
	s_nop 0
	global_load_dwordx4 v[22:25], v[22:23], off
	s_nop 0
	global_load_dwordx4 v[26:29], v[30:31], off offset:16
	s_nop 0
	global_load_dwordx4 v[30:33], v[30:31], off
	v_ashrrev_i32_e32 v35, 31, v34
	s_mov_b32 s4, 0x200
	v_add_u32_e32 v50, s4, v8
	v_ashrrev_i32_e32 v50, 4, v50
	v_add_u32_e32 v84, s16, v50
	v_lshl_or_b32 v68, v84, 5, v2
	v_add_u32_e32 v50, s2, v50
	v_ashrrev_i32_e32 v69, 31, v68
	v_mad_i64_i32 v[64:65], s[0:1], v50, s84, v[4:5]
	v_lshlrev_b64 v[68:69], 2, v[68:69]
	global_load_dwordx4 v[60:63], v[64:65], off
	s_nop 0
	global_load_dwordx4 v[64:67], v[64:65], off offset:64
	v_lshl_add_u64 v[72:73], s[8:9], 0, v[68:69]
	v_lshl_add_u64 v[80:81], s[10:11], 0, v[68:69]
	global_load_dwordx4 v[68:71], v[72:73], off offset:16
	s_nop 0
	global_load_dwordx4 v[72:75], v[72:73], off
	s_nop 0
	global_load_dwordx4 v[76:79], v[80:81], off offset:16
	s_nop 0
	global_load_dwordx4 v[80:83], v[80:81], off
	v_ashrrev_i32_e32 v85, 31, v84
	s_waitcnt vmcnt(6)
	v_lshlrev_b32_e32 v36, 16, v10
	v_and_b32_e32 v37, 0xffff0000, v10
	v_lshlrev_b32_e32 v38, 16, v14
	v_and_b32_e32 v39, 0xffff0000, v14
	v_pk_mul_f32 v[40:41], v[30:31], v[38:39]
	v_pk_mul_f32 v[30:31], v[30:31], v[36:37]
	v_lshlrev_b32_e32 v14, 16, v15
	v_and_b32_e32 v15, 0xffff0000, v15
	v_pk_fma_f32 v[40:41], v[22:23], v[36:37], v[40:41] neg_lo:[0,0,1] neg_hi:[0,0,1]
	v_pk_fma_f32 v[22:23], v[22:23], v[38:39], v[30:31]
	v_lshlrev_b32_e32 v10, 16, v11
	v_and_b32_e32 v11, 0xffff0000, v11
	v_pk_mul_f32 v[30:31], v[32:33], v[14:15]
	s_nop 0
	v_pk_fma_f32 v[30:31], v[24:25], v[10:11], v[30:31] neg_lo:[0,0,1] neg_hi:[0,0,1]
	v_pk_mul_f32 v[10:11], v[32:33], v[10:11]
	s_nop 0
	v_pk_fma_f32 v[14:15], v[24:25], v[14:15], v[10:11]
	v_lshlrev_b32_e32 v24, 16, v16
	v_and_b32_e32 v25, 0xffff0000, v16
	v_lshlrev_b32_e32 v10, 16, v12
	v_and_b32_e32 v11, 0xffff0000, v12
	v_pk_mul_f32 v[32:33], v[26:27], v[24:25]
	v_lshlrev_b32_e32 v12, 16, v17
	v_pk_fma_f32 v[32:33], v[18:19], v[10:11], v[32:33] neg_lo:[0,0,1] neg_hi:[0,0,1]
	v_pk_mul_f32 v[10:11], v[26:27], v[10:11]
	s_nop 0
	v_pk_fma_f32 v[18:19], v[18:19], v[24:25], v[10:11]
	v_lshlrev_b32_e32 v10, 16, v13
	v_and_b32_e32 v11, 0xffff0000, v13
	v_and_b32_e32 v13, 0xffff0000, v17
	v_pk_mul_f32 v[16:17], v[28:29], v[12:13]
	s_nop 0
	v_pk_fma_f32 v[16:17], v[20:21], v[10:11], v[16:17] neg_lo:[0,0,1] neg_hi:[0,0,1]
	v_pk_mul_f32 v[10:11], v[28:29], v[10:11]
	s_nop 0
	v_pk_fma_f32 v[20:21], v[20:21], v[12:13], v[10:11]
	v_lshlrev_b64 v[10:11], 7, v[34:35]
	v_lshl_add_u64 v[24:25], v[6:7], 0, v[10:11]
	v_cvt_pk_bf16_f32 v10, v40, v41
	v_cvt_pk_bf16_f32 v11, v30, v31
	v_cvt_pk_bf16_f32 v12, v32, v33
	v_cvt_pk_bf16_f32 v13, v16, v17
	global_store_dwordx4 v[24:25], v[10:13], off
	s_nop 1
	v_cvt_pk_bf16_f32 v10, v22, v23
	v_cvt_pk_bf16_f32 v11, v14, v15
	v_cvt_pk_bf16_f32 v12, v18, v19
	v_cvt_pk_bf16_f32 v13, v20, v21
	global_store_dwordx4 v[24:25], v[10:13], off offset:64
	s_waitcnt vmcnt(2)
	v_lshlrev_b32_e32 v86, 16, v60
	v_and_b32_e32 v87, 0xffff0000, v60
	v_lshlrev_b32_e32 v88, 16, v64
	v_and_b32_e32 v89, 0xffff0000, v64
	v_pk_mul_f32 v[90:91], v[80:81], v[88:89]
	v_pk_mul_f32 v[80:81], v[80:81], v[86:87]
	v_lshlrev_b32_e32 v64, 16, v65
	v_and_b32_e32 v65, 0xffff0000, v65
	v_pk_fma_f32 v[90:91], v[72:73], v[86:87], v[90:91] neg_lo:[0,0,1] neg_hi:[0,0,1]
	v_pk_fma_f32 v[72:73], v[72:73], v[88:89], v[80:81]
	v_lshlrev_b32_e32 v60, 16, v61
	v_and_b32_e32 v61, 0xffff0000, v61
	v_pk_mul_f32 v[80:81], v[82:83], v[64:65]
	s_nop 0
	v_pk_fma_f32 v[80:81], v[74:75], v[60:61], v[80:81] neg_lo:[0,0,1] neg_hi:[0,0,1]
	v_pk_mul_f32 v[60:61], v[82:83], v[60:61]
	s_nop 0
	v_pk_fma_f32 v[64:65], v[74:75], v[64:65], v[60:61]
	v_lshlrev_b32_e32 v74, 16, v66
	v_and_b32_e32 v75, 0xffff0000, v66
	v_lshlrev_b32_e32 v60, 16, v62
	v_and_b32_e32 v61, 0xffff0000, v62
	v_pk_mul_f32 v[82:83], v[76:77], v[74:75]
	v_lshlrev_b32_e32 v62, 16, v67
	v_pk_fma_f32 v[82:83], v[68:69], v[60:61], v[82:83] neg_lo:[0,0,1] neg_hi:[0,0,1]
	v_pk_mul_f32 v[60:61], v[76:77], v[60:61]
	s_nop 0
	v_pk_fma_f32 v[68:69], v[68:69], v[74:75], v[60:61]
	v_lshlrev_b32_e32 v60, 16, v63
	v_and_b32_e32 v61, 0xffff0000, v63
	v_and_b32_e32 v63, 0xffff0000, v67
	v_pk_mul_f32 v[66:67], v[78:79], v[62:63]
	s_nop 0
	v_pk_fma_f32 v[66:67], v[70:71], v[60:61], v[66:67] neg_lo:[0,0,1] neg_hi:[0,0,1]
	v_pk_mul_f32 v[60:61], v[78:79], v[60:61]
	s_nop 0
	v_pk_fma_f32 v[70:71], v[70:71], v[62:63], v[60:61]
	v_lshlrev_b64 v[60:61], 7, v[84:85]
	v_lshl_add_u64 v[74:75], v[6:7], 0, v[60:61]
	v_cvt_pk_bf16_f32 v60, v90, v91
	v_cvt_pk_bf16_f32 v61, v80, v81
	v_cvt_pk_bf16_f32 v62, v82, v83
	v_cvt_pk_bf16_f32 v63, v66, v67
	global_store_dwordx4 v[74:75], v[60:63], off
	s_nop 1
	v_cvt_pk_bf16_f32 v60, v72, v73
	v_cvt_pk_bf16_f32 v61, v64, v65
	v_cvt_pk_bf16_f32 v62, v68, v69
	v_cvt_pk_bf16_f32 v63, v70, v71
	global_store_dwordx4 v[74:75], v[60:63], off offset:64
	s_movk_i32 s4, 0x200
	s_mov_b64 s[0:1], 0
	s_mov_b64 vcc, exec
	v_ashrrev_i32_e32 v4, 3, v8
	v_add_u32_e32 v0, s2, v4
	v_mov_b64_e32 v[2:3], s[50:51]
	v_and_b32_e32 v6, 7, v8
	v_mad_i64_i32 v[2:3], s[0:1], v0, s84, v[2:3]
	v_and_b32_e32 v0, 56, v9
	v_mul_lo_u32 v5, v4, s45
	v_lshlrev_b32_e32 v7, 4, v6
	v_add3_u32 v5, v5, v7, 0
	s_mov_b32 s0, 0
	v_lshlrev_b32_e32 v0, 1, v0
	s_mov_b32 s1, 0
